# v61 + x->int8 conversion fast path (wave-contiguous 8KiB chunks, double buffered)
# baseline (speedup 1.0000x reference)
; #define LAS __attribute__((address_space(3)))
;     if (ldw == 0) ldw = N;
;     LAS float* scr = (LAS float*)(F.lds + F.wave * 16384); const int lane = F.lane;
;     const int nblk = N / 32, nitems = (K / 64) * nblk;
;     for (int item = F.gw; item < nitems; item += F.NGW) { const int kb = item / nblk, nb = item % nblk, k0 = 64 * kb, n0 = 32 * nb;
;         int dr0 = n0; if (MAP == 1) { if (n0 < DFF) dr0 = (n0 >> 7) * 256 + (n0 & 127); else { const int uo = n0 - DFF; dr0 = (uo >> 7) * 256 + 128 + (uo & 127); } }
; #pragma unroll 8
;         for (int i = 0; i < 32; ++i) { const int kk = 2 * i + (lane >> 5); scr[kk * 33 + (lane & 31)] = W[(size_t)(k0 + kk) * ldw + n0 + (lane & 31)]; }
; __device__ __forceinline__ void p0_prologue(Frame& F) {
;     ...
;     transpose_f8_matrix<1, true>(F, F.in[I_F1IN], D, NFF, F.ws + WS_WFI, I8_W);
.Lx8_done:
	s_lshr_b32 s0, s86, 6
	s_lshl_b32 s79, s2, 3
	s_add_i32 s94, s0, s79
	s_lshl_b32 s92, s96, 3
	s_cmp_lt_i32 s94, 0xac00
	v_and_b32_e32 v178, 63, v0
	v_writelane_b32 v240, s0, 2
	s_cselect_b64 s[0:1], -1, 0
	v_writelane_b32 v240, s0, 3
	s_cmp_gt_i32 s94, 0xabff
	v_lshrrev_b32_e32 v162, 5, v178
	v_and_b32_e32 v164, 31, v0
	v_lshrrev_b32_e32 v163, 2, v178
	v_lshlrev_b32_e32 v167, 4, v0
	v_and_b32_e32 v165, 60, v178
	v_writelane_b32 v240, s1, 4
	s_cbranch_scc1 .LBB0_20
	s_barrier
	s_load_dwordx2 s[50:51], s[74:75], 0x38
	v_readlane_b32 s16, v240, 2
	v_lshlrev_b32_e32 v212, 4, v178
	v_mov_b32_e32 v216, 0x42fe0000
	s_mov_b32 s36, 0x44fe0000
	s_mov_b32 s37, 0
	s_mov_b32 s38, 0x4b400000
	s_mov_b32 s39, 0
	s_mov_b32 s40, 0xc2fe0000
	s_mov_b32 s41, 0x0c0c0400
	s_mov_b32 s42, 0x05040100
	s_lshl_b32 s17, s16, 5
	s_and_b32 s18, s16, 4
	s_lshl_b32 s18, s18, 5
	s_add_i32 s17, s17, s18
	v_mul_u32_u24_e32 v213, 0x240, v178
	s_lshl_b32 s18, s16, 4
	v_add_u32_e32 v213, s18, v213
	v_lshrrev_b32_e32 v204, 3, v178
	v_and_b32_e32 v205, 7, v178
	s_lshl_b32 s18, s16, 5
	v_add_u32_e32 v206, s18, v204
	v_mul_u32_u24_e32 v214, 0x90, v206
	v_lshl_add_u32 v214, v205, 4, v214
	v_mul_u32_u24_e32 v215, 0x1000, v204
	v_lshl_add_u32 v215, v205, 4, v215
	s_lshl_b32 s16, s16, 4
	s_waitcnt lgkmcnt(0)
	s_add_u32 s44, s90, 0x8300000
	s_addc_u32 s45, s91, 0
	s_mov_b32 s19, s2
	s_cmp_lt_u32 s19, 0xac0
	s_cbranch_scc0 .Lf8t_f1in0_end
	s_mul_hi_u32 s20, s19, 0x2fa0be9
	s_mul_i32 s21, s20, 86
	s_sub_i32 s21, s19, s21
	s_lshl_b32 s60, s20, 7
	s_lshl_b32 s61, s21, 8
	s_add_i32 s24, s60, s16
	s_mul_i32 s24, s24, 0x15800
	s_lshl_b32 s25, s61, 2
	s_add_u32 s24, s24, s25
	s_add_u32 s52, s50, s24
	s_addc_u32 s53, s51, 0
	global_load_dwordx4 v[80:83], v212, s[52:53]
	s_add_u32 s52, s52, 0x15800
	s_addc_u32 s53, s53, 0
	global_load_dwordx4 v[84:87], v212, s[52:53]
	s_add_u32 s52, s52, 0x15800
	s_addc_u32 s53, s53, 0
	global_load_dwordx4 v[88:91], v212, s[52:53]
	s_add_u32 s52, s52, 0x15800
	s_addc_u32 s53, s53, 0
	global_load_dwordx4 v[92:95], v212, s[52:53]
	s_add_u32 s52, s52, 0x15800
	s_addc_u32 s53, s53, 0
	global_load_dwordx4 v[96:99], v212, s[52:53]
	s_add_u32 s52, s52, 0x15800
	s_addc_u32 s53, s53, 0
	global_load_dwordx4 v[100:103], v212, s[52:53]
	s_add_u32 s52, s52, 0x15800
	s_addc_u32 s53, s53, 0
	global_load_dwordx4 v[104:107], v212, s[52:53]
	s_add_u32 s52, s52, 0x15800
	s_addc_u32 s53, s53, 0
	global_load_dwordx4 v[108:111], v212, s[52:53]
	s_add_u32 s52, s52, 0x15800
	s_addc_u32 s53, s53, 0
	global_load_dwordx4 v[112:115], v212, s[52:53]
	s_add_u32 s52, s52, 0x15800
	s_addc_u32 s53, s53, 0
	global_load_dwordx4 v[116:119], v212, s[52:53]
	s_add_u32 s52, s52, 0x15800
	s_addc_u32 s53, s53, 0
	global_load_dwordx4 v[120:123], v212, s[52:53]
	s_add_u32 s52, s52, 0x15800
	s_addc_u32 s53, s53, 0
	global_load_dwordx4 v[124:127], v212, s[52:53]
	s_add_u32 s52, s52, 0x15800
	s_addc_u32 s53, s53, 0
	global_load_dwordx4 v[128:131], v212, s[52:53]
	s_add_u32 s52, s52, 0x15800
	s_addc_u32 s53, s53, 0
	global_load_dwordx4 v[132:135], v212, s[52:53]
	s_add_u32 s52, s52, 0x15800
	s_addc_u32 s53, s53, 0
	global_load_dwordx4 v[136:139], v212, s[52:53]
	s_add_u32 s52, s52, 0x15800
	s_addc_u32 s53, s53, 0
	global_load_dwordx4 v[140:143], v212, s[52:53]
	s_mov_b32 s58, 1
